# v2 + barrier leader bumps XCD generation before its own invalidate + second w_ple_proj transpose call on workgroups 64..127
# speedup vs baseline: 1.0038x; 1.0038x over previous
; #define LAS __attribute__((address_space(3)))
; template <bool REMAP = false>
; __device__ __forceinline__ void transpose_convert(LAS unsigned char* lds, const float* src, bf16_t* dst, int K, int N, int G, int bid) {
;     LAS float* tile = (LAS float*)lds;
;     const int tid = threadIdx.x, ntn = N / 64, ntiles = (K / 128) * ntn;
;     const int r0 = tid >> 4, c4 = tid & 15;
;     f32x4 v[4];
;     if (bid < ntiles) { const int k0 = (bid / ntn) * 128, n0 = (bid % ntn) * 64;
; #pragma unroll
;         for (int i = 0; i < 4; ++i) v[i] = __builtin_nontemporal_load((const f32x4*)(src + (size_t)(k0 + r0 + 32 * i) * N + n0 + c4 * 4)); }
;     for (int t = bid; t < ntiles; t += G) {
;         const int k0 = (t / ntn) * 128, n0 = (t % ntn) * 64;
;         asm volatile("s_waitcnt lgkmcnt(0)" ::: "memory"); __builtin_amdgcn_s_barrier(); asm volatile("" ::: "memory");
; #pragma unroll
;         for (int i = 0; i < 4; ++i) {
; #pragma unroll
;             for (int j = 0; j < 4; ++j) tile[(r0 + 32 * i) * 65 + c4 * 4 + j] = v[i][j]; }
;         asm volatile("s_waitcnt lgkmcnt(0)" ::: "memory"); __builtin_amdgcn_s_barrier(); asm volatile("" ::: "memory");
;         if (t + G < ntiles) { const int k1 = ((t + G) / ntn) * 128, n1 = ((t + G) % ntn) * 64;
; #pragma unroll
;             for (int i = 0; i < 4; ++i) v[i] = __builtin_nontemporal_load((const f32x4*)(src + (size_t)(k1 + r0 + 32 * i) * N + n1 + c4 * 4)); }
; __global__ void __launch_bounds__(NTHREADS, 2) mk_fwd(Params P) {
;     ...
;         transpose_convert(lds, P.w_proj, WP, 256, 2048, G, bid);
;         transpose_convert(lds, P.w_proj + (size_t)256 * 2048, WP + (size_t)2048 * 256, 256, 2048, G, bid);
.LBB0_41:
	s_sub_i32 s99, s2, 64
	s_cmp_lt_u32 s99, 64
	s_cselect_b64 s[0:1], -1, 0
	s_andn2_b64 vcc, exec, s[0:1]
	s_barrier
	s_cbranch_vccnz .LBB0_48
	s_add_u32 s0, s36, 0x200000
	s_addc_u32 s1, s37, 0
	s_ashr_i32 s3, s99, 31
	s_lshr_b32 s3, s3, 27
	s_add_i32 s3, s99, s3
	s_lshl_b32 s4, s3, 2
	s_and_b32 s3, s3, 0x3ffffe0
	s_sub_i32 s3, s99, s3
	s_and_b32 s5, s4, 0xffffff80
	s_lshl_b32 s4, s3, 6
	s_waitcnt vmcnt(3)
	v_or_b32_e32 v8, s5, v214
	s_ashr_i32 s5, s4, 31
	s_lshl_b64 s[4:5], s[4:5], 2
	v_and_b32_e32 v21, 15, v164
	s_add_u32 s4, s0, s4
	s_addc_u32 s5, s1, s5
	v_lshlrev_b32_e32 v18, 4, v21
	v_mov_b32_e32 v19, 0
	v_ashrrev_i32_e32 v9, 31, v8
	v_lshl_add_u64 v[10:11], s[4:5], 0, v[18:19]
	v_lshlrev_b64 v[0:1], 13, v[8:9]
	s_waitcnt vmcnt(2)
	v_lshl_add_u64 v[12:13], v[10:11], 0, v[0:1]
	s_mov_b32 s3, 0x40000
	v_add_co_u32_e32 v4, vcc, s3, v12
	v_or_b32_e32 v8, 64, v8
	s_nop 0
	v_addc_co_u32_e32 v5, vcc, 0, v13, vcc
	v_ashrrev_i32_e32 v9, 31, v8
	s_mov_b32 s6, 0xc0000
	global_load_dwordx4 v[0:3], v[12:13], off nt
	s_nop 0
	global_load_dwordx4 v[4:7], v[4:5], off nt
	v_lshlrev_b64 v[8:9], 13, v[8:9]
	v_add_co_u32_e32 v12, vcc, s6, v12
	v_lshl_add_u64 v[8:9], v[10:11], 0, v[8:9]
	s_nop 0
	v_addc_co_u32_e32 v13, vcc, 0, v13, vcc
	global_load_dwordx4 v[8:11], v[8:9], off nt
	s_nop 0
	global_load_dwordx4 v[12:15], v[12:13], off nt
	v_add_u32_e32 v20, 0x200, v164
	v_add_u32_e32 v22, 0, v18
	v_lshrrev_b32_e32 v20, 4, v20
	v_mul_u32_u24_e32 v28, 0x820, v21
	v_mul_u32_u24_e32 v21, 0x104, v214
	v_lshl_add_u64 v[16:17], s[0:1], 0, v[18:19]
	v_lshl_add_u64 v[18:19], s[40:41], 0, v[18:19]
	s_mov_b64 s[0:1], 0x3100000
	v_lshl_add_u32 v27, v20, 2, 0
	v_add_u32_e32 v21, v22, v21
	v_lshl_add_u64 v[18:19], v[18:19], 0, s[0:1]
	s_lshl_b32 s10, s99, 6
	s_lshl_b32 s7, s34, 6
	v_add_u32_e32 v22, 0x2080, v21
	v_add_u32_e32 v23, 0x2088, v21
	v_add_u32_e32 v25, 0x4100, v21
	v_add_u32_e32 v26, v24, v28
	v_add_u32_e32 v27, v27, v28
	v_add_u32_e32 v28, 0x4108, v21
	v_add_u32_e32 v29, 0x6180, v21
	s_mov_b32 s11, s99
	s_branch .LBB0_44

; __device__ __forceinline__ unsigned xb_ld(unsigned* p)              { return __hip_atomic_load(p, __ATOMIC_RELAXED, __HIP_MEMORY_SCOPE_AGENT); }
; __device__ __forceinline__ unsigned xb_add(unsigned* p, unsigned v) { return __hip_atomic_fetch_add(p, v, __ATOMIC_RELAXED, __HIP_MEMORY_SCOPE_AGENT); }
; #define XB_SPIN(cond, bar) do { unsigned _sp = 0; while (cond) { __builtin_amdgcn_s_sleep(1); \
;     if ((++_sp & 255u) == 0u) { if (xb_ld(&(bar)[XB_TMO])) break; if (_sp > XB_SPIN_CAP) { atomicAdd(&(bar)[XB_TMO], 1u); break; } } } } while (0)
; __device__ __forceinline__ void xcd_barrier(const XcdBarrier& b) {
;     ...
;             const unsigned og = xb_add(&bar[XB_TOP], 1u);
;             const unsigned tg = og / nx;
;             if (og + 1u == (tg + 1u) * nx) xb_add(&bar[XB_TOPGEN], 1u);
;             else XB_SPIN(xb_ld(&bar[XB_TOPGEN]) == tg, bar);
;             __builtin_amdgcn_fence(__ATOMIC_ACQUIRE, "agent");
;             xb_add(&bar[XB_XGEN(b.x)], 1u);
;             asm volatile("s_waitcnt vmcnt(0)" ::: "memory");
.LBB0_141:
	s_or_b64 exec, exec, s[8:9]
	v_mov_b32_e32 v0, 0x2000
	v_mov_b32_e32 v1, 1
	s_waitcnt vmcnt(0)
	global_atomic_add v0, v1, s[6:7] offset:1024
	buffer_inv sc1
	s_waitcnt vmcnt(0)

; __device__ __forceinline__ unsigned xb_ld(unsigned* p)              { return __hip_atomic_load(p, __ATOMIC_RELAXED, __HIP_MEMORY_SCOPE_AGENT); }
; __device__ __forceinline__ unsigned xb_add(unsigned* p, unsigned v) { return __hip_atomic_fetch_add(p, v, __ATOMIC_RELAXED, __HIP_MEMORY_SCOPE_AGENT); }
; #define XB_SPIN(cond, bar) do { unsigned _sp = 0; while (cond) { __builtin_amdgcn_s_sleep(1); \
;     if ((++_sp & 255u) == 0u) { if (xb_ld(&(bar)[XB_TMO])) break; if (_sp > XB_SPIN_CAP) { atomicAdd(&(bar)[XB_TMO], 1u); break; } } } } while (0)
; __device__ __forceinline__ void xcd_barrier(const XcdBarrier& b) {
;     ...
;             const unsigned og = xb_add(&bar[XB_TOP], 1u);
;             const unsigned tg = og / nx;
;             if (og + 1u == (tg + 1u) * nx) xb_add(&bar[XB_TOPGEN], 1u);
;             else XB_SPIN(xb_ld(&bar[XB_TOPGEN]) == tg, bar);
;             __builtin_amdgcn_fence(__ATOMIC_ACQUIRE, "agent");
;             xb_add(&bar[XB_XGEN(b.x)], 1u);
;             asm volatile("s_waitcnt vmcnt(0)" ::: "memory");
.LBB0_230:
	s_or_b64 exec, exec, s[18:19]
	v_mov_b32_e32 v0, 0x2000
	v_mov_b32_e32 v1, 1
	s_waitcnt vmcnt(0)
	global_atomic_add v0, v1, s[6:7] offset:1024
	buffer_inv sc1
	s_waitcnt vmcnt(0)

; __device__ __forceinline__ unsigned xb_ld(unsigned* p)              { return __hip_atomic_load(p, __ATOMIC_RELAXED, __HIP_MEMORY_SCOPE_AGENT); }
; __device__ __forceinline__ unsigned xb_add(unsigned* p, unsigned v) { return __hip_atomic_fetch_add(p, v, __ATOMIC_RELAXED, __HIP_MEMORY_SCOPE_AGENT); }
; #define XB_SPIN(cond, bar) do { unsigned _sp = 0; while (cond) { __builtin_amdgcn_s_sleep(1); \
;     if ((++_sp & 255u) == 0u) { if (xb_ld(&(bar)[XB_TMO])) break; if (_sp > XB_SPIN_CAP) { atomicAdd(&(bar)[XB_TMO], 1u); break; } } } } while (0)
; __device__ __forceinline__ void xcd_barrier(const XcdBarrier& b) {
;     ...
;             const unsigned og = xb_add(&bar[XB_TOP], 1u);
;             const unsigned tg = og / nx;
;             if (og + 1u == (tg + 1u) * nx) xb_add(&bar[XB_TOPGEN], 1u);
;             else XB_SPIN(xb_ld(&bar[XB_TOPGEN]) == tg, bar);
;             __builtin_amdgcn_fence(__ATOMIC_ACQUIRE, "agent");
;             xb_add(&bar[XB_XGEN(b.x)], 1u);
;             asm volatile("s_waitcnt vmcnt(0)" ::: "memory");
.LBB0_289:
	s_or_b64 exec, exec, s[16:17]
	v_mov_b32_e32 v0, 0x2000
	v_mov_b32_e32 v1, 1
	s_waitcnt vmcnt(0)
	global_atomic_add v0, v1, s[6:7] offset:1024
	buffer_inv sc1
	s_waitcnt vmcnt(0)

; __device__ __forceinline__ unsigned xb_ld(unsigned* p)              { return __hip_atomic_load(p, __ATOMIC_RELAXED, __HIP_MEMORY_SCOPE_AGENT); }
; __device__ __forceinline__ unsigned xb_add(unsigned* p, unsigned v) { return __hip_atomic_fetch_add(p, v, __ATOMIC_RELAXED, __HIP_MEMORY_SCOPE_AGENT); }
; #define XB_SPIN(cond, bar) do { unsigned _sp = 0; while (cond) { __builtin_amdgcn_s_sleep(1); \
;     if ((++_sp & 255u) == 0u) { if (xb_ld(&(bar)[XB_TMO])) break; if (_sp > XB_SPIN_CAP) { atomicAdd(&(bar)[XB_TMO], 1u); break; } } } } while (0)
; __device__ __forceinline__ void xcd_barrier(const XcdBarrier& b) {
;     ...
;             const unsigned og = xb_add(&bar[XB_TOP], 1u);
;             const unsigned tg = og / nx;
;             if (og + 1u == (tg + 1u) * nx) xb_add(&bar[XB_TOPGEN], 1u);
;             else XB_SPIN(xb_ld(&bar[XB_TOPGEN]) == tg, bar);
;             __builtin_amdgcn_fence(__ATOMIC_ACQUIRE, "agent");
;             xb_add(&bar[XB_XGEN(b.x)], 1u);
;             asm volatile("s_waitcnt vmcnt(0)" ::: "memory");
.LBB0_414:
	s_or_b64 exec, exec, s[6:7]
	v_mov_b32_e32 v0, 0x2000
	v_mov_b32_e32 v1, 1
	s_waitcnt vmcnt(0)
	global_atomic_add v0, v1, s[4:5] offset:1024
	buffer_inv sc1
	s_waitcnt vmcnt(0)

; __device__ __forceinline__ unsigned xb_ld(unsigned* p)              { return __hip_atomic_load(p, __ATOMIC_RELAXED, __HIP_MEMORY_SCOPE_AGENT); }
; __device__ __forceinline__ unsigned xb_add(unsigned* p, unsigned v) { return __hip_atomic_fetch_add(p, v, __ATOMIC_RELAXED, __HIP_MEMORY_SCOPE_AGENT); }
; #define XB_SPIN(cond, bar) do { unsigned _sp = 0; while (cond) { __builtin_amdgcn_s_sleep(1); \
;     if ((++_sp & 255u) == 0u) { if (xb_ld(&(bar)[XB_TMO])) break; if (_sp > XB_SPIN_CAP) { atomicAdd(&(bar)[XB_TMO], 1u); break; } } } } while (0)
; __device__ __forceinline__ void xcd_barrier(const XcdBarrier& b) {
;     ...
;             const unsigned og = xb_add(&bar[XB_TOP], 1u);
;             const unsigned tg = og / nx;
;             if (og + 1u == (tg + 1u) * nx) xb_add(&bar[XB_TOPGEN], 1u);
;             else XB_SPIN(xb_ld(&bar[XB_TOPGEN]) == tg, bar);
;             __builtin_amdgcn_fence(__ATOMIC_ACQUIRE, "agent");
;             xb_add(&bar[XB_XGEN(b.x)], 1u);
;             asm volatile("s_waitcnt vmcnt(0)" ::: "memory");
.LBB0_619:
	s_or_b64 exec, exec, s[10:11]
	v_mov_b32_e32 v0, 0x2000
	v_mov_b32_e32 v1, 1
	s_waitcnt vmcnt(0)
	global_atomic_add v0, v1, s[8:9] offset:1024
	buffer_inv sc1
	s_waitcnt vmcnt(0)
